# P5 epilogue: per-panel rstd cached in VGPRs (ssq loads+reductions once per 4 tiles)
# speedup vs baseline: 1.0045x; 1.0040x over previous
; #define PG8_STAGE(bufoff, gbase, voff) do { _Pragma("unroll") for (int _i = 0; _i < 2; ++_i) { unsigned vo_ = (voff)[_i]; if constexpr (FP8) asm volatile("" : "+v"(vo_)); \
;         __builtin_amdgcn_global_load_lds((const unsigned*)((const char*)(gbase) + vo_), (PG8_LAS unsigned*)(lds + (bufoff) + ldsw + _i * 8192), 16, 0, 0); } } while (0)
; #define PG8_WAIT_V(n) asm volatile("s_waitcnt vmcnt(" #n ")" ::: "memory")
; #define PG8_BAR __builtin_amdgcn_s_barrier()
; template <class Epi, class Sched, bool ALIGN_EPI = false, bool SP2 = false, bool FP8 = false>
; __device__ __forceinline__ void gemm_phase(PG8_LAS unsigned char* lds, const Gemm g, const Sched& S, const Epi& E) {
;     ...
;     const int tid = tid_l, wid = __builtin_amdgcn_readfirstlane(tid >> 6), lane = tid & 63, wr = wid >> 2, wc = wid & 3, fr = lane & 15, fq = lane >> 4;
;     const int K = g.K, nt = K / BK;
;     unsigned voffA[2], voffB[2];
; #pragma unroll
;     for (int i = 0; i < 2; ++i) { int R, C; stage_rc(tid * 16 + i * 8192, R, C); const int Rb = Epi::PERM ? ((R & ~31) + perm32(R & 31)) : R;
;         voffA[i] = (unsigned)(R * K + C) * 2u; voffB[i] = (unsigned)(Rb * K + C) * 2u; }
;     const size_t kstep = (size_t)(BK * 2);
;     const size_t hstep = (size_t)HALF * K * 2;
;     const size_t tstep = 2 * hstep;
;     const unsigned ldsw = (unsigned)wid * 1024u;
;     const int aoff = lds_byte(wr * 64 + fr, fq * 8), boff = lds_byte(wc * 32 + fr, fq * 8);
;     ...
;     const char* cA = (const char*)g.A + (size_t)cur.pm * tstep; const char* cB = (const char*)g.Bt + (size_t)cur.pn * tstep;
;     S.a_ready(cur);
;     if constexpr (SP2) {
;         PG8_STAGE(PG8_SB(0, 0), cB, voffB); PG8_STAGE(PG8_SB(0, 1), cB + hstep, voffB); PG8_STAGE(PG8_SA(0, 0), cA, voffA); PG8_STAGE(PG8_SA(0, 1), cA + hstep, voffA);
;         if (wr == 1) PG8_BAR;
;         PG8_WAIT_V(2); PG8_BAR;
.LBB0_382:
	s_or_b64 exec, exec, s[4:5]
	s_mov_b32 s101, -1
	v_mov_b32_e32 v10, v254
	s_barrier
	s_cmpk_lt_i32 s33, 0x1400
	s_nop 0
	v_readfirstlane_b32 s5, v10
	s_cbranch_scc0 .LBB0_398
	v_lshlrev_b32_e32 v0, 4, v10
	v_add_u32_e32 v1, 0x2000, v0
	v_ashrrev_i32_e32 v2, 31, v1
	v_lshrrev_b32_e32 v2, 22, v2
	v_add_u32_e32 v2, v1, v2
	v_ashrrev_i32_e32 v8, 10, v2
	v_mul_i32_i24_e32 v2, 0x400, v8
	v_sub_u32_e32 v1, v1, v2
	v_lshrrev_b32_e32 v2, 4, v1
	v_bitop3_b32 v1, v2, v1, 32 bitop3:0x6c
	v_ashrrev_i32_e32 v2, 31, v1
	v_lshrrev_b32_e32 v2, 26, v2
	v_add_u32_e32 v2, v1, v2
	v_lshlrev_b32_e32 v3, 3, v8
	v_ashrrev_i32_e32 v9, 6, v2
	v_and_b32_e32 v3, -16, v3
	v_add_u32_e32 v3, v9, v3
	v_and_b32_e32 v4, 3, v9
	s_mov_b32 s0, 0x1fffe0
	v_lshrrev_b32_e32 v5, 2, v3
	v_lshlrev_b32_e32 v6, 1, v3
	v_and_b32_e32 v2, 0xc0, v2
	v_and_or_b32 v4, v3, s0, v4
	v_and_b32_e32 v5, 4, v5
	v_and_b32_e32 v6, 24, v6
	v_sub_u32_e32 v1, v1, v2
	v_mov_b32_e32 v2, 1
	v_or3_b32 v4, v4, v5, v6
	v_lshlrev_b32_e32 v5, 5, v8
	v_ashrrev_i16_sdwa v1, v2, sext(v1) dst_sel:DWORD dst_unused:UNUSED_PAD src0_sel:DWORD src1_sel:BYTE_0
	v_and_b32_e32 v5, 32, v5
	v_bfe_i32 v11, v1, 0, 16
	v_add_lshl_u32 v1, v5, v11, 1
	v_lshl_add_u32 v128, v4, 11, v1
	v_lshl_add_u32 v130, v3, 11, v1
	v_bfe_i32 v1, v10, 27, 1
	v_lshrrev_b32_e32 v1, 22, v1
	v_add_u32_e32 v1, v0, v1
	v_and_b32_e32 v1, 0xfffffc00, v1
	v_sub_u32_e32 v0, v0, v1
	v_lshrrev_b32_e32 v1, 4, v0
	v_ashrrev_i32_e32 v3, 31, v10
	v_bitop3_b32 v0, v1, v0, 32 bitop3:0x6c
	v_lshrrev_b32_e32 v3, 26, v3
	v_ashrrev_i32_e32 v1, 31, v0
	v_add_u32_e32 v3, v10, v3
	v_lshrrev_b32_e32 v1, 26, v1
	v_ashrrev_i32_e32 v13, 6, v3
	v_add_u32_e32 v1, v0, v1
	v_lshlrev_b32_e32 v3, 3, v13
	v_ashrrev_i32_e32 v12, 6, v1
	v_and_b32_e32 v3, -16, v3
	v_add_u32_e32 v3, v12, v3
	v_and_b32_e32 v4, 3, v12
	v_and_or_b32 v4, v3, s0, v4
	s_ashr_i32 s0, s33, 31
	s_lshr_b32 s0, s0, 29
	s_add_i32 s0, s33, s0
	s_ashr_i32 s8, s5, 6
	s_ashr_i32 s1, s0, 3
	s_and_b32 s0, s0, -8
	s_ashr_i32 s10, s5, 8
	s_lshl_b32 s46, s8, 10
	s_sub_i32 s0, s33, s0
	s_cmp_lt_i32 s0, 0
	s_movk_i32 s47, 0x281
	s_cselect_b32 s4, s47, 0x280
	s_mul_i32 s0, s0, s4
	s_add_i32 s0, s0, s1
	s_ashr_i32 s1, s0, 31
	s_lshr_b32 s1, s1, 25
	s_add_i32 s1, s0, s1
	s_ashr_i32 s4, s1, 7
	s_and_b32 s1, s1, 0xff80
	s_sub_i32 s0, s0, s1
	s_bfe_i32 s1, s0, 0x80000
	s_bfe_u32 s1, s1, 0x3000c
	s_add_i32 s1, s0, s1
	s_lshl_b32 s6, s4, 3
	s_bfe_i32 s4, s1, 0x80000
	s_and_b32 s1, s1, 0xf8
	s_sub_i32 s0, s0, s1
	s_sext_i32_i16 s4, s4
	s_sext_i32_i8 s0, s0
	v_lshrrev_b32_e32 v5, 2, v3
	v_lshlrev_b32_e32 v6, 1, v3
	v_and_b32_e32 v1, 0xc0, v1
	s_lshr_b32 s4, s4, 3
	s_add_i32 s38, s6, s0
	v_and_b32_e32 v5, 4, v5
	v_and_b32_e32 v6, 24, v6
	v_sub_u32_e32 v0, v0, v1
	s_ashr_i32 s39, s38, 31
	s_bfe_i64 s[6:7], s[4:5], 0x100000
	v_or3_b32 v4, v4, v5, v6
	v_lshlrev_b32_e32 v5, 5, v13
	v_ashrrev_i16_sdwa v0, v2, sext(v0) dst_sel:DWORD dst_unused:UNUSED_PAD src0_sel:DWORD src1_sel:BYTE_0
	s_lshl_b64 s[0:1], s[38:39], 19
	s_lshl_b64 s[6:7], s[6:7], 19
	v_and_b32_e32 v5, 32, v5
	v_bfe_i32 v14, v0, 0, 16
	s_add_u32 s42, s30, s6
	v_add_lshl_u32 v0, v5, v14, 1
	s_addc_u32 s43, s31, s7
	s_add_i32 s39, s46, 0
	v_lshl_add_u32 v132, v4, 11, v0
	s_add_i32 m0, s39, 0x10000
	v_lshl_add_u32 v134, v3, 11, v0
	global_load_lds_dwordx4 v132, s[42:43]
	s_add_i32 m0, s39, 0x12000
	s_add_u32 s6, s42, 0x40000
	global_load_lds_dwordx4 v128, s[42:43]
	s_addc_u32 s7, s43, 0
	s_add_i32 m0, s39, 0x14000
	v_mov_b32_e32 v133, 0
	global_load_lds_dwordx4 v132, s[6:7]
	s_add_i32 m0, s39, 0x16000
	s_add_u32 s40, s16, s0
	s_addc_u32 s41, s17, s1
	s_add_i32 s48, s39, 0x2000
	global_load_lds_dwordx4 v128, s[6:7]
	s_mov_b32 m0, s39
	s_add_u32 s0, s40, 0x40000
	global_load_lds_dwordx4 v134, s[40:41]
	s_mov_b32 m0, s48
	s_addc_u32 s1, s41, 0
	s_add_i32 s49, s39, 0x4000
	global_load_lds_dwordx4 v130, s[40:41]
	s_mov_b32 m0, s49
	s_add_i32 s50, s39, 0x6000
	global_load_lds_dwordx4 v134, s[0:1]
	s_mov_b32 m0, s50
	v_mov_b32_e32 v129, v133
	global_load_lds_dwordx4 v130, s[0:1]
	v_mov_b32_e32 v135, v133
	v_mov_b32_e32 v131, v133
	s_cmp_eq_u32 s10, 1
	s_mov_b32 s51, 0
	v_lshl_add_u64 v[6:7], s[42:43], 0, v[132:133]
	v_lshl_add_u64 v[4:5], s[42:43], 0, v[128:129]
	v_lshl_add_u64 v[0:1], s[40:41], 0, v[134:135]
	s_cselect_b64 s[6:7], -1, 0
	s_cmp_lg_u32 s10, 1
	v_lshl_add_u64 v[2:3], s[40:41], 0, v[130:131]
	s_cbranch_scc1 .LBB0_385
	s_barrier

;     __device__ __forceinline__ void operator()(const f32x4 (&acc)[2][2][4][2], const Unit& u, int wr, int wc, int fr, int fq) const {
;     ...
;             for (int m = 0; m < 4; ++m) { const size_t r = (size_t)(row0 + ai * HALF + m * 16);
;                 const f32x4 pq = *(const f32x4*)(ssq + r * 16 + 4 * fq);
;                 float ss = (pq[0] + pq[1]) + (pq[2] + pq[3]); ss += __shfl_xor(ss, 16); ss += __shfl_xor(ss, 32);
;                 const float rs = __builtin_amdgcn_rsqf(ss * (1.f / DM) + RMS_EPS);
; #pragma unroll
;                 for (int bj = 0; bj < 2; ++bj) { f32x4 v0 = acc[ai][bj][m][0] * rs, v1 = acc[ai][bj][m][1] * rs;
.LBB0_394:
	s_cmp_eq_u32 s38, s101
	s_cbranch_scc1 .Lmy_rs_cached
	s_mov_b32 s101, s38
	v_lshl_add_u32 v204, s38, 8, v150
	v_ashrrev_i32_e32 v205, 31, v204
	v_lshlrev_b64 v[204:205], 6, v[204:205]
	v_lshl_add_u64 v[204:205], v[136:137], 0, v[204:205]
	s_mov_b64 s[0:1], 0x2000
	global_load_dwordx4 v[170:173], v[204:205], off
	global_load_dwordx4 v[174:177], v[204:205], off offset:1024
	global_load_dwordx4 v[178:181], v[204:205], off offset:2048
	global_load_dwordx4 v[182:185], v[204:205], off offset:3072
	v_lshl_add_u64 v[206:207], v[204:205], 0, s[0:1]
	global_load_dwordx4 v[186:189], v[206:207], off
	global_load_dwordx4 v[190:193], v[206:207], off offset:1024
	global_load_dwordx4 v[194:197], v[206:207], off offset:2048
	global_load_dwordx4 v[198:201], v[206:207], off offset:3072
	v_and_b32_e32 v210, 64, v156
	v_add_u32_e32 v210, 64, v210
	v_xor_b32_e32 v208, 16, v156
	v_cmp_lt_i32_e32 vcc, v208, v210
	s_nop 1
	v_cndmask_b32_e32 v208, v156, v208, vcc
	v_lshlrev_b32_e32 v208, 2, v208
	v_xor_b32_e32 v209, 32, v156
	v_cmp_lt_i32_e32 vcc, v209, v210
	s_nop 1
	v_cndmask_b32_e32 v209, v156, v209, vcc
	v_lshlrev_b32_e32 v209, 2, v209
	s_waitcnt vmcnt(7)
	v_add_f32_e32 v204, v170, v171
	v_add_f32_e32 v205, v172, v173
	v_add_f32_e32 v204, v204, v205
	ds_bpermute_b32 v205, v208, v204
	s_waitcnt lgkmcnt(0)
	v_add_f32_e32 v204, v204, v205
	ds_bpermute_b32 v205, v209, v204
	s_waitcnt lgkmcnt(0)
	v_add_f32_e32 v204, v204, v205
	v_fmamk_f32 v204, v204, 0x3a800000, v157
	v_rsq_f32_e32 v228, v204
	s_waitcnt vmcnt(6)
	v_add_f32_e32 v204, v174, v175
	v_add_f32_e32 v205, v176, v177
	v_add_f32_e32 v204, v204, v205
	ds_bpermute_b32 v205, v208, v204
	s_waitcnt lgkmcnt(0)
	v_add_f32_e32 v204, v204, v205
	ds_bpermute_b32 v205, v209, v204
	s_waitcnt lgkmcnt(0)
	v_add_f32_e32 v204, v204, v205
	v_fmamk_f32 v204, v204, 0x3a800000, v157
	v_rsq_f32_e32 v229, v204
	s_waitcnt vmcnt(5)
	v_add_f32_e32 v204, v178, v179
	v_add_f32_e32 v205, v180, v181
	v_add_f32_e32 v204, v204, v205
	ds_bpermute_b32 v205, v208, v204
	s_waitcnt lgkmcnt(0)
	v_add_f32_e32 v204, v204, v205
	ds_bpermute_b32 v205, v209, v204
	s_waitcnt lgkmcnt(0)
	v_add_f32_e32 v204, v204, v205
	v_fmamk_f32 v204, v204, 0x3a800000, v157
	v_rsq_f32_e32 v230, v204
	s_waitcnt vmcnt(4)
	v_add_f32_e32 v204, v182, v183
	v_add_f32_e32 v205, v184, v185
	v_add_f32_e32 v204, v204, v205
	ds_bpermute_b32 v205, v208, v204
	s_waitcnt lgkmcnt(0)
	v_add_f32_e32 v204, v204, v205
	ds_bpermute_b32 v205, v209, v204
	s_waitcnt lgkmcnt(0)
	v_add_f32_e32 v204, v204, v205
	v_fmamk_f32 v204, v204, 0x3a800000, v157
	v_rsq_f32_e32 v231, v204
	s_waitcnt vmcnt(3)
	v_add_f32_e32 v204, v186, v187
	v_add_f32_e32 v205, v188, v189
	v_add_f32_e32 v204, v204, v205
	ds_bpermute_b32 v205, v208, v204
	s_waitcnt lgkmcnt(0)
	v_add_f32_e32 v204, v204, v205
	ds_bpermute_b32 v205, v209, v204
	s_waitcnt lgkmcnt(0)
	v_add_f32_e32 v204, v204, v205
	v_fmamk_f32 v204, v204, 0x3a800000, v157
	v_rsq_f32_e32 v232, v204
	s_waitcnt vmcnt(2)
	v_add_f32_e32 v204, v190, v191
	v_add_f32_e32 v205, v192, v193
	v_add_f32_e32 v204, v204, v205
	ds_bpermute_b32 v205, v208, v204
	s_waitcnt lgkmcnt(0)
	v_add_f32_e32 v204, v204, v205
	ds_bpermute_b32 v205, v209, v204
	s_waitcnt lgkmcnt(0)
	v_add_f32_e32 v204, v204, v205
	v_fmamk_f32 v204, v204, 0x3a800000, v157
	v_rsq_f32_e32 v233, v204
	s_waitcnt vmcnt(1)
	v_add_f32_e32 v204, v194, v195
	v_add_f32_e32 v205, v196, v197
	v_add_f32_e32 v204, v204, v205
	ds_bpermute_b32 v205, v208, v204
	s_waitcnt lgkmcnt(0)
	v_add_f32_e32 v204, v204, v205
	ds_bpermute_b32 v205, v209, v204
	s_waitcnt lgkmcnt(0)
	v_add_f32_e32 v204, v204, v205
	v_fmamk_f32 v204, v204, 0x3a800000, v157
	v_rsq_f32_e32 v234, v204
	s_waitcnt vmcnt(0)
	v_add_f32_e32 v204, v198, v199
	v_add_f32_e32 v205, v200, v201
	v_add_f32_e32 v204, v204, v205
	ds_bpermute_b32 v205, v208, v204
	s_waitcnt lgkmcnt(0)
	v_add_f32_e32 v204, v204, v205
	ds_bpermute_b32 v205, v209, v204
	s_waitcnt lgkmcnt(0)
	v_add_f32_e32 v204, v204, v205
	v_fmamk_f32 v204, v204, 0x3a800000, v157
	v_rsq_f32_e32 v235, v204
	s_nop 0
.Lmy_rs_cached:
	v_lshl_add_u32 v148, s38, 8, v150
	v_ashrrev_i32_e32 v149, 31, v148
	v_lshlrev_b64 v[146:147], 6, v[148:149]
	v_lshl_add_u64 v[146:147], v[136:137], 0, v[146:147]
	v_and_b32_e32 v147, 64, v156
	v_xor_b32_e32 v158, 16, v156
	v_add_u32_e32 v166, 64, v147
	v_cmp_lt_i32_e32 vcc, v158, v166
	v_xor_b32_e32 v159, 32, v156
	v_lshl_or_b32 v146, s56, 8, v152
	v_cndmask_b32_e32 v158, v156, v158, vcc
	v_lshlrev_b32_e32 v158, 2, v158
	v_cmp_lt_i32_e32 vcc, v159, v166
	v_ashrrev_i32_e32 v147, 31, v146
	v_lshlrev_b64 v[146:147], 1, v[146:147]
	v_cndmask_b32_e32 v159, v156, v159, vcc
	v_lshlrev_b32_e32 v159, 2, v159
	s_andn2_b64 vcc, exec, s[4:5]
	s_mov_b64 s[4:5], -1
	v_or_b32_e32 v160, 16, v148
	v_lshlrev_b64 v[162:163], 13, v[148:149]
	v_ashrrev_i32_e32 v161, 31, v160
	v_lshl_add_u64 v[162:163], s[28:29], 0, v[162:163]
	v_lshlrev_b64 v[166:167], 6, v[160:161]
	v_mov_b32_e32 v164, v228
	v_lshl_add_u64 v[162:163], v[162:163], 0, v[146:147]
	v_lshl_add_u64 v[166:167], v[136:137], 0, v[166:167]
	v_pk_mul_f32 v[126:127], v[126:127], v[164:165] op_sel_hi:[1,0]
	v_pk_mul_f32 v[124:125], v[124:125], v[164:165] op_sel_hi:[1,0]
	v_pk_mul_f32 v[122:123], v[122:123], v[164:165] op_sel_hi:[1,0]
	v_pk_mul_f32 v[120:121], v[120:121], v[164:165] op_sel_hi:[1,0]
	v_pk_mul_f32 v[118:119], v[118:119], v[164:165] op_sel_hi:[1,0]
	v_pk_mul_f32 v[116:117], v[116:117], v[164:165] op_sel_hi:[1,0]
	v_pk_mul_f32 v[114:115], v[114:115], v[164:165] op_sel_hi:[1,0]
	v_pk_mul_f32 v[112:113], v[112:113], v[164:165] op_sel_hi:[1,0]
	v_max_f32_e32 v124, 0, v124
	v_max_f32_e32 v120, 0, v120
	v_max_f32_e32 v125, 0, v125
; __device__ __forceinline__ unsigned cvt_pk_bf16(float lo, float hi) { const f32x2c_t v = {lo, hi}; const bf16x2c_t b = __builtin_convertvector(v, bf16x2c_t); return __builtin_bit_cast(unsigned, b); }
;     __device__ __forceinline__ void operator()(const f32x4 (&acc)[2][2][4][2], const Unit& u, int wr, int wc, int fr, int fq) const {
;     ...
;             for (int m = 0; m < 4; ++m) { const size_t r = (size_t)(row0 + ai * HALF + m * 16);
;                 const f32x4 pq = *(const f32x4*)(ssq + r * 16 + 4 * fq);
;                 float ss = (pq[0] + pq[1]) + (pq[2] + pq[3]); ss += __shfl_xor(ss, 16); ss += __shfl_xor(ss, 32);
;                 const float rs = __builtin_amdgcn_rsqf(ss * (1.f / DM) + RMS_EPS);
; #pragma unroll
;                 for (int bj = 0; bj < 2; ++bj) { f32x4 v0 = acc[ai][bj][m][0] * rs, v1 = acc[ai][bj][m][1] * rs;
; #pragma unroll
;                     for (int e = 0; e < 4; ++e) { const float a = fmaxf(v0[e], 0.f), b = fmaxf(v1[e], 0.f); v0[e] = a * a; v1[e] = b * b; }
;                     u32x4 w; w.x = cvt_pk_bf16(v0[0], v0[1]); w.y = cvt_pk_bf16(v0[2], v0[3]); w.z = cvt_pk_bf16(v1[0], v1[1]); w.w = cvt_pk_bf16(v1[2], v1[3]);
;                     *(u32x4*)(O + r * DFF + col0 + bj * HALF) = w; } }
	v_max_f32_e32 v121, 0, v121
	v_max_f32_e32 v126, 0, v126
	v_max_f32_e32 v122, 0, v122
	v_max_f32_e32 v127, 0, v127
	v_max_f32_e32 v123, 0, v123
	v_max_f32_e32 v116, 0, v116
	v_max_f32_e32 v112, 0, v112
	v_max_f32_e32 v117, 0, v117
	v_max_f32_e32 v113, 0, v113
	v_max_f32_e32 v118, 0, v118
	v_max_f32_e32 v114, 0, v114
	v_max_f32_e32 v119, 0, v119
	v_max_f32_e32 v115, 0, v115
	v_pk_mul_f32 v[124:125], v[124:125], v[124:125]
	v_pk_mul_f32 v[120:121], v[120:121], v[120:121]
	v_pk_mul_f32 v[126:127], v[126:127], v[126:127]
	v_pk_mul_f32 v[122:123], v[122:123], v[122:123]
	v_pk_mul_f32 v[116:117], v[116:117], v[116:117]
	v_pk_mul_f32 v[164:165], v[112:113], v[112:113]
	v_pk_mul_f32 v[118:119], v[118:119], v[118:119]
	v_pk_mul_f32 v[168:169], v[114:115], v[114:115]
	v_cvt_pk_bf16_f32 v112, v124, v125
	v_cvt_pk_bf16_f32 v113, v126, v127
	v_cvt_pk_bf16_f32 v114, v120, v121
	v_cvt_pk_bf16_f32 v115, v122, v123
	v_cvt_pk_bf16_f32 v116, v116, v117
	v_cvt_pk_bf16_f32 v117, v118, v119
	v_cvt_pk_bf16_f32 v118, v164, v165
	v_cvt_pk_bf16_f32 v119, v168, v169
	global_store_dwordx4 v[162:163], v[112:115], off
	global_store_dwordx4 v[162:163], v[116:119], off offset:256
	v_lshlrev_b64 v[114:115], 13, v[160:161]
	v_lshl_add_u64 v[114:115], s[28:29], 0, v[114:115]
	v_lshl_add_u64 v[114:115], v[114:115], 0, v[146:147]
	v_or_b32_e32 v112, 32, v148
	v_ashrrev_i32_e32 v113, 31, v112
	v_lshlrev_b64 v[116:117], 6, v[112:113]
	v_lshl_add_u64 v[116:117], v[136:137], 0, v[116:117]
	v_mov_b32_e32 v118, v229
	s_nop 0
	v_pk_mul_f32 v[110:111], v[110:111], v[118:119] op_sel_hi:[1,0]
	v_pk_mul_f32 v[108:109], v[108:109], v[118:119] op_sel_hi:[1,0]
	v_pk_mul_f32 v[106:107], v[106:107], v[118:119] op_sel_hi:[1,0]
	v_pk_mul_f32 v[104:105], v[104:105], v[118:119] op_sel_hi:[1,0]
	v_pk_mul_f32 v[102:103], v[102:103], v[118:119] op_sel_hi:[1,0]
	v_pk_mul_f32 v[100:101], v[100:101], v[118:119] op_sel_hi:[1,0]
	v_pk_mul_f32 v[98:99], v[98:99], v[118:119] op_sel_hi:[1,0]
	v_pk_mul_f32 v[96:97], v[96:97], v[118:119] op_sel_hi:[1,0]
	v_max_f32_e32 v108, 0, v108
	v_max_f32_e32 v104, 0, v104
	v_max_f32_e32 v109, 0, v109
	v_max_f32_e32 v105, 0, v105
	v_max_f32_e32 v110, 0, v110
	v_max_f32_e32 v106, 0, v106
	v_max_f32_e32 v111, 0, v111
	v_max_f32_e32 v107, 0, v107
	v_max_f32_e32 v100, 0, v100
	v_max_f32_e32 v96, 0, v96
	v_max_f32_e32 v101, 0, v101
	v_max_f32_e32 v97, 0, v97
	v_max_f32_e32 v102, 0, v102
	v_max_f32_e32 v98, 0, v98
	v_max_f32_e32 v103, 0, v103
	v_max_f32_e32 v99, 0, v99
	v_pk_mul_f32 v[108:109], v[108:109], v[108:109]
	v_pk_mul_f32 v[104:105], v[104:105], v[104:105]
	v_pk_mul_f32 v[110:111], v[110:111], v[110:111]
	v_pk_mul_f32 v[106:107], v[106:107], v[106:107]
	v_pk_mul_f32 v[100:101], v[100:101], v[100:101]
	v_pk_mul_f32 v[118:119], v[96:97], v[96:97]
	v_pk_mul_f32 v[102:103], v[102:103], v[102:103]
	v_pk_mul_f32 v[120:121], v[98:99], v[98:99]
	v_cvt_pk_bf16_f32 v96, v108, v109
	v_cvt_pk_bf16_f32 v97, v110, v111
	v_cvt_pk_bf16_f32 v98, v104, v105
	v_cvt_pk_bf16_f32 v99, v106, v107
	v_cvt_pk_bf16_f32 v100, v100, v101
	v_cvt_pk_bf16_f32 v101, v102, v103
	v_cvt_pk_bf16_f32 v102, v118, v119
	v_cvt_pk_bf16_f32 v103, v120, v121
	global_store_dwordx4 v[114:115], v[96:99], off
	global_store_dwordx4 v[114:115], v[100:103], off offset:256
	v_lshlrev_b64 v[98:99], 13, v[112:113]
	v_lshl_add_u64 v[98:99], s[28:29], 0, v[98:99]
	v_lshl_add_u64 v[98:99], v[98:99], 0, v[146:147]
	v_or_b32_e32 v96, 48, v148
	v_ashrrev_i32_e32 v97, 31, v96
	v_lshlrev_b64 v[100:101], 6, v[96:97]
	v_lshl_add_u64 v[100:101], v[136:137], 0, v[100:101]
	v_mov_b32_e32 v102, v230
	s_nop 0
	v_pk_mul_f32 v[94:95], v[94:95], v[102:103] op_sel_hi:[1,0]
	v_pk_mul_f32 v[92:93], v[92:93], v[102:103] op_sel_hi:[1,0]
	v_pk_mul_f32 v[90:91], v[90:91], v[102:103] op_sel_hi:[1,0]
	v_pk_mul_f32 v[88:89], v[88:89], v[102:103] op_sel_hi:[1,0]
	v_pk_mul_f32 v[86:87], v[86:87], v[102:103] op_sel_hi:[1,0]
	v_pk_mul_f32 v[84:85], v[84:85], v[102:103] op_sel_hi:[1,0]
	v_pk_mul_f32 v[82:83], v[82:83], v[102:103] op_sel_hi:[1,0]
	v_pk_mul_f32 v[80:81], v[80:81], v[102:103] op_sel_hi:[1,0]
	v_max_f32_e32 v92, 0, v92
	v_max_f32_e32 v88, 0, v88
	v_max_f32_e32 v93, 0, v93
	v_max_f32_e32 v89, 0, v89
	v_max_f32_e32 v94, 0, v94
	v_max_f32_e32 v90, 0, v90
	v_max_f32_e32 v95, 0, v95
	v_max_f32_e32 v91, 0, v91
	v_max_f32_e32 v84, 0, v84
	v_max_f32_e32 v80, 0, v80
	v_max_f32_e32 v85, 0, v85
	v_max_f32_e32 v81, 0, v81
	v_max_f32_e32 v86, 0, v86
	v_max_f32_e32 v82, 0, v82
	v_max_f32_e32 v87, 0, v87
	v_max_f32_e32 v83, 0, v83
	v_pk_mul_f32 v[92:93], v[92:93], v[92:93]
	v_pk_mul_f32 v[88:89], v[88:89], v[88:89]
	v_pk_mul_f32 v[94:95], v[94:95], v[94:95]
	v_pk_mul_f32 v[90:91], v[90:91], v[90:91]
	v_pk_mul_f32 v[84:85], v[84:85], v[84:85]
	v_pk_mul_f32 v[102:103], v[80:81], v[80:81]
	v_pk_mul_f32 v[86:87], v[86:87], v[86:87]
	v_pk_mul_f32 v[104:105], v[82:83], v[82:83]
	v_cvt_pk_bf16_f32 v80, v92, v93
	v_cvt_pk_bf16_f32 v81, v94, v95
	v_cvt_pk_bf16_f32 v82, v88, v89
	v_cvt_pk_bf16_f32 v83, v90, v91
	v_cvt_pk_bf16_f32 v84, v84, v85
	v_cvt_pk_bf16_f32 v85, v86, v87
	v_cvt_pk_bf16_f32 v86, v102, v103
	v_cvt_pk_bf16_f32 v87, v104, v105
	global_store_dwordx4 v[98:99], v[80:83], off
	global_store_dwordx4 v[98:99], v[84:87], off offset:256
	v_lshlrev_b64 v[82:83], 13, v[96:97]
	v_lshl_add_u64 v[82:83], s[28:29], 0, v[82:83]
	v_lshl_add_u64 v[82:83], v[82:83], 0, v[146:147]
	v_add_u32_e32 v80, 0x80, v148
	v_ashrrev_i32_e32 v81, 31, v80
	v_lshlrev_b64 v[84:85], 6, v[80:81]
	v_lshl_add_u64 v[84:85], v[136:137], 0, v[84:85]
	v_mov_b32_e32 v86, v231
	s_nop 0
	v_pk_mul_f32 v[78:79], v[78:79], v[86:87] op_sel_hi:[1,0]
	v_pk_mul_f32 v[76:77], v[76:77], v[86:87] op_sel_hi:[1,0]
; __device__ __forceinline__ unsigned cvt_pk_bf16(float lo, float hi) { const f32x2c_t v = {lo, hi}; const bf16x2c_t b = __builtin_convertvector(v, bf16x2c_t); return __builtin_bit_cast(unsigned, b); }
;     __device__ __forceinline__ void operator()(const f32x4 (&acc)[2][2][4][2], const Unit& u, int wr, int wc, int fr, int fq) const {
;     ...
;             for (int m = 0; m < 4; ++m) { const size_t r = (size_t)(row0 + ai * HALF + m * 16);
;                 const f32x4 pq = *(const f32x4*)(ssq + r * 16 + 4 * fq);
;                 float ss = (pq[0] + pq[1]) + (pq[2] + pq[3]); ss += __shfl_xor(ss, 16); ss += __shfl_xor(ss, 32);
;                 const float rs = __builtin_amdgcn_rsqf(ss * (1.f / DM) + RMS_EPS);
; #pragma unroll
;                 for (int bj = 0; bj < 2; ++bj) { f32x4 v0 = acc[ai][bj][m][0] * rs, v1 = acc[ai][bj][m][1] * rs;
; #pragma unroll
;                     for (int e = 0; e < 4; ++e) { const float a = fmaxf(v0[e], 0.f), b = fmaxf(v1[e], 0.f); v0[e] = a * a; v1[e] = b * b; }
;                     u32x4 w; w.x = cvt_pk_bf16(v0[0], v0[1]); w.y = cvt_pk_bf16(v0[2], v0[3]); w.z = cvt_pk_bf16(v1[0], v1[1]); w.w = cvt_pk_bf16(v1[2], v1[3]);
;                     *(u32x4*)(O + r * DFF + col0 + bj * HALF) = w; } }
	v_pk_mul_f32 v[74:75], v[74:75], v[86:87] op_sel_hi:[1,0]
	v_pk_mul_f32 v[72:73], v[72:73], v[86:87] op_sel_hi:[1,0]
	v_pk_mul_f32 v[70:71], v[70:71], v[86:87] op_sel_hi:[1,0]
	v_pk_mul_f32 v[68:69], v[68:69], v[86:87] op_sel_hi:[1,0]
	v_pk_mul_f32 v[66:67], v[66:67], v[86:87] op_sel_hi:[1,0]
	v_pk_mul_f32 v[64:65], v[64:65], v[86:87] op_sel_hi:[1,0]
	v_max_f32_e32 v76, 0, v76
	v_max_f32_e32 v72, 0, v72
	v_max_f32_e32 v77, 0, v77
	v_max_f32_e32 v73, 0, v73
	v_max_f32_e32 v78, 0, v78
	v_max_f32_e32 v74, 0, v74
	v_max_f32_e32 v79, 0, v79
	v_max_f32_e32 v75, 0, v75
	v_max_f32_e32 v68, 0, v68
	v_max_f32_e32 v64, 0, v64
	v_max_f32_e32 v69, 0, v69
	v_max_f32_e32 v65, 0, v65
	v_max_f32_e32 v70, 0, v70
	v_max_f32_e32 v66, 0, v66
	v_max_f32_e32 v71, 0, v71
	v_max_f32_e32 v67, 0, v67
	v_pk_mul_f32 v[76:77], v[76:77], v[76:77]
	v_pk_mul_f32 v[72:73], v[72:73], v[72:73]
	v_pk_mul_f32 v[78:79], v[78:79], v[78:79]
	v_pk_mul_f32 v[74:75], v[74:75], v[74:75]
	v_pk_mul_f32 v[68:69], v[68:69], v[68:69]
	v_pk_mul_f32 v[86:87], v[64:65], v[64:65]
	v_pk_mul_f32 v[70:71], v[70:71], v[70:71]
	v_pk_mul_f32 v[88:89], v[66:67], v[66:67]
	v_cvt_pk_bf16_f32 v64, v76, v77
	v_cvt_pk_bf16_f32 v65, v78, v79
	v_cvt_pk_bf16_f32 v66, v72, v73
	v_cvt_pk_bf16_f32 v67, v74, v75
	v_cvt_pk_bf16_f32 v68, v68, v69
	v_cvt_pk_bf16_f32 v69, v70, v71
	v_cvt_pk_bf16_f32 v70, v86, v87
	v_cvt_pk_bf16_f32 v71, v88, v89
	global_store_dwordx4 v[82:83], v[64:67], off
	global_store_dwordx4 v[82:83], v[68:71], off offset:256
	v_lshlrev_b64 v[66:67], 13, v[80:81]
	v_lshl_add_u64 v[66:67], s[28:29], 0, v[66:67]
	v_lshl_add_u64 v[66:67], v[66:67], 0, v[146:147]
	v_add_u32_e32 v64, 0x90, v148
	v_ashrrev_i32_e32 v65, 31, v64
	v_lshlrev_b64 v[68:69], 6, v[64:65]
	v_lshl_add_u64 v[68:69], v[136:137], 0, v[68:69]
	v_mov_b32_e32 v70, v232
	s_nop 0
	v_pk_mul_f32 v[62:63], v[62:63], v[70:71] op_sel_hi:[1,0]
	v_pk_mul_f32 v[60:61], v[60:61], v[70:71] op_sel_hi:[1,0]
	v_pk_mul_f32 v[58:59], v[58:59], v[70:71] op_sel_hi:[1,0]
	v_pk_mul_f32 v[56:57], v[56:57], v[70:71] op_sel_hi:[1,0]
	v_pk_mul_f32 v[54:55], v[54:55], v[70:71] op_sel_hi:[1,0]
	v_pk_mul_f32 v[52:53], v[52:53], v[70:71] op_sel_hi:[1,0]
	v_pk_mul_f32 v[50:51], v[50:51], v[70:71] op_sel_hi:[1,0]
	v_pk_mul_f32 v[48:49], v[48:49], v[70:71] op_sel_hi:[1,0]
	v_max_f32_e32 v60, 0, v60
	v_max_f32_e32 v56, 0, v56
	v_max_f32_e32 v61, 0, v61
	v_max_f32_e32 v57, 0, v57
	v_max_f32_e32 v62, 0, v62
	v_max_f32_e32 v58, 0, v58
	v_max_f32_e32 v63, 0, v63
	v_max_f32_e32 v59, 0, v59
	v_max_f32_e32 v52, 0, v52
	v_max_f32_e32 v48, 0, v48
	v_max_f32_e32 v53, 0, v53
	v_max_f32_e32 v49, 0, v49
	v_max_f32_e32 v54, 0, v54
	v_max_f32_e32 v50, 0, v50
	v_max_f32_e32 v55, 0, v55
	v_max_f32_e32 v51, 0, v51
	v_pk_mul_f32 v[60:61], v[60:61], v[60:61]
	v_pk_mul_f32 v[56:57], v[56:57], v[56:57]
	v_pk_mul_f32 v[62:63], v[62:63], v[62:63]
	v_pk_mul_f32 v[58:59], v[58:59], v[58:59]
	v_pk_mul_f32 v[52:53], v[52:53], v[52:53]
	v_pk_mul_f32 v[70:71], v[48:49], v[48:49]
	v_pk_mul_f32 v[54:55], v[54:55], v[54:55]
	v_pk_mul_f32 v[72:73], v[50:51], v[50:51]
	v_cvt_pk_bf16_f32 v48, v60, v61
	v_cvt_pk_bf16_f32 v49, v62, v63
	v_cvt_pk_bf16_f32 v50, v56, v57
	v_cvt_pk_bf16_f32 v51, v58, v59
	v_cvt_pk_bf16_f32 v52, v52, v53
	v_cvt_pk_bf16_f32 v53, v54, v55
	v_cvt_pk_bf16_f32 v54, v70, v71
	v_cvt_pk_bf16_f32 v55, v72, v73
	global_store_dwordx4 v[66:67], v[48:51], off
	global_store_dwordx4 v[66:67], v[52:55], off offset:256
	v_lshlrev_b64 v[50:51], 13, v[64:65]
	v_lshl_add_u64 v[50:51], s[28:29], 0, v[50:51]
	v_lshl_add_u64 v[50:51], v[50:51], 0, v[146:147]
	v_add_u32_e32 v48, 0xa0, v148
	v_ashrrev_i32_e32 v49, 31, v48
	v_lshlrev_b64 v[52:53], 6, v[48:49]
	v_lshl_add_u64 v[52:53], v[136:137], 0, v[52:53]
	v_mov_b32_e32 v54, v233
	s_nop 0
	v_pk_mul_f32 v[46:47], v[46:47], v[54:55] op_sel_hi:[1,0]
	v_pk_mul_f32 v[44:45], v[44:45], v[54:55] op_sel_hi:[1,0]
	v_pk_mul_f32 v[42:43], v[42:43], v[54:55] op_sel_hi:[1,0]
	v_pk_mul_f32 v[40:41], v[40:41], v[54:55] op_sel_hi:[1,0]
	v_pk_mul_f32 v[38:39], v[38:39], v[54:55] op_sel_hi:[1,0]
	v_pk_mul_f32 v[36:37], v[36:37], v[54:55] op_sel_hi:[1,0]
	v_pk_mul_f32 v[34:35], v[34:35], v[54:55] op_sel_hi:[1,0]
	v_pk_mul_f32 v[32:33], v[32:33], v[54:55] op_sel_hi:[1,0]
	v_max_f32_e32 v44, 0, v44
	v_max_f32_e32 v40, 0, v40
	v_max_f32_e32 v45, 0, v45
	v_max_f32_e32 v41, 0, v41
	v_max_f32_e32 v46, 0, v46
	v_max_f32_e32 v42, 0, v42
	v_max_f32_e32 v47, 0, v47
	v_max_f32_e32 v43, 0, v43
	v_max_f32_e32 v36, 0, v36
	v_max_f32_e32 v32, 0, v32
	v_max_f32_e32 v37, 0, v37
	v_max_f32_e32 v33, 0, v33
	v_max_f32_e32 v38, 0, v38
; __device__ __forceinline__ unsigned cvt_pk_bf16(float lo, float hi) { const f32x2c_t v = {lo, hi}; const bf16x2c_t b = __builtin_convertvector(v, bf16x2c_t); return __builtin_bit_cast(unsigned, b); }
;     __device__ __forceinline__ void operator()(const f32x4 (&acc)[2][2][4][2], const Unit& u, int wr, int wc, int fr, int fq) const {
;     ...
;             for (int m = 0; m < 4; ++m) { const size_t r = (size_t)(row0 + ai * HALF + m * 16);
;                 const f32x4 pq = *(const f32x4*)(ssq + r * 16 + 4 * fq);
;                 float ss = (pq[0] + pq[1]) + (pq[2] + pq[3]); ss += __shfl_xor(ss, 16); ss += __shfl_xor(ss, 32);
;                 const float rs = __builtin_amdgcn_rsqf(ss * (1.f / DM) + RMS_EPS);
; #pragma unroll
;                 for (int bj = 0; bj < 2; ++bj) { f32x4 v0 = acc[ai][bj][m][0] * rs, v1 = acc[ai][bj][m][1] * rs;
; #pragma unroll
;                     for (int e = 0; e < 4; ++e) { const float a = fmaxf(v0[e], 0.f), b = fmaxf(v1[e], 0.f); v0[e] = a * a; v1[e] = b * b; }
;                     u32x4 w; w.x = cvt_pk_bf16(v0[0], v0[1]); w.y = cvt_pk_bf16(v0[2], v0[3]); w.z = cvt_pk_bf16(v1[0], v1[1]); w.w = cvt_pk_bf16(v1[2], v1[3]);
;                     *(u32x4*)(O + r * DFF + col0 + bj * HALF) = w; } }
	v_max_f32_e32 v34, 0, v34
	v_max_f32_e32 v39, 0, v39
	v_max_f32_e32 v35, 0, v35
	v_pk_mul_f32 v[44:45], v[44:45], v[44:45]
	v_pk_mul_f32 v[40:41], v[40:41], v[40:41]
	v_pk_mul_f32 v[46:47], v[46:47], v[46:47]
	v_pk_mul_f32 v[42:43], v[42:43], v[42:43]
	v_pk_mul_f32 v[36:37], v[36:37], v[36:37]
	v_pk_mul_f32 v[54:55], v[32:33], v[32:33]
	v_pk_mul_f32 v[38:39], v[38:39], v[38:39]
	v_pk_mul_f32 v[56:57], v[34:35], v[34:35]
	v_cvt_pk_bf16_f32 v32, v44, v45
	v_cvt_pk_bf16_f32 v33, v46, v47
	v_cvt_pk_bf16_f32 v34, v40, v41
	v_cvt_pk_bf16_f32 v35, v42, v43
	v_cvt_pk_bf16_f32 v36, v36, v37
	v_cvt_pk_bf16_f32 v37, v38, v39
	v_cvt_pk_bf16_f32 v38, v54, v55
	v_cvt_pk_bf16_f32 v39, v56, v57
	global_store_dwordx4 v[50:51], v[32:35], off
	global_store_dwordx4 v[50:51], v[36:39], off offset:256
	v_lshlrev_b64 v[34:35], 13, v[48:49]
	v_lshl_add_u64 v[34:35], s[28:29], 0, v[34:35]
	v_lshl_add_u64 v[34:35], v[34:35], 0, v[146:147]
	v_add_u32_e32 v32, 0xb0, v148
	v_ashrrev_i32_e32 v33, 31, v32
	v_lshlrev_b64 v[36:37], 6, v[32:33]
	v_lshl_add_u64 v[36:37], v[136:137], 0, v[36:37]
	v_mov_b32_e32 v38, v234
	s_nop 0
	v_pk_mul_f32 v[30:31], v[30:31], v[38:39] op_sel_hi:[1,0]
	v_pk_mul_f32 v[28:29], v[28:29], v[38:39] op_sel_hi:[1,0]
	v_pk_mul_f32 v[26:27], v[26:27], v[38:39] op_sel_hi:[1,0]
	v_pk_mul_f32 v[24:25], v[24:25], v[38:39] op_sel_hi:[1,0]
	v_pk_mul_f32 v[22:23], v[22:23], v[38:39] op_sel_hi:[1,0]
	v_pk_mul_f32 v[20:21], v[20:21], v[38:39] op_sel_hi:[1,0]
	v_pk_mul_f32 v[18:19], v[18:19], v[38:39] op_sel_hi:[1,0]
	v_pk_mul_f32 v[16:17], v[16:17], v[38:39] op_sel_hi:[1,0]
	v_max_f32_e32 v28, 0, v28
	v_max_f32_e32 v24, 0, v24
	v_max_f32_e32 v29, 0, v29
	v_max_f32_e32 v25, 0, v25
	v_max_f32_e32 v30, 0, v30
	v_max_f32_e32 v26, 0, v26
	v_max_f32_e32 v31, 0, v31
	v_max_f32_e32 v27, 0, v27
	v_max_f32_e32 v20, 0, v20
	v_max_f32_e32 v16, 0, v16
	v_max_f32_e32 v21, 0, v21
	v_max_f32_e32 v17, 0, v17
	v_max_f32_e32 v22, 0, v22
	v_max_f32_e32 v18, 0, v18
	v_max_f32_e32 v23, 0, v23
	v_max_f32_e32 v19, 0, v19
	v_pk_mul_f32 v[28:29], v[28:29], v[28:29]
	v_pk_mul_f32 v[24:25], v[24:25], v[24:25]
	v_pk_mul_f32 v[30:31], v[30:31], v[30:31]
	v_pk_mul_f32 v[26:27], v[26:27], v[26:27]
	v_pk_mul_f32 v[20:21], v[20:21], v[20:21]
	v_pk_mul_f32 v[38:39], v[16:17], v[16:17]
	v_pk_mul_f32 v[22:23], v[22:23], v[22:23]
	v_pk_mul_f32 v[40:41], v[18:19], v[18:19]
	v_cvt_pk_bf16_f32 v16, v28, v29
	v_cvt_pk_bf16_f32 v17, v30, v31
	v_cvt_pk_bf16_f32 v18, v24, v25
	v_cvt_pk_bf16_f32 v19, v26, v27
	v_cvt_pk_bf16_f32 v20, v20, v21
	v_cvt_pk_bf16_f32 v21, v22, v23
	v_cvt_pk_bf16_f32 v22, v38, v39
	v_cvt_pk_bf16_f32 v23, v40, v41
	global_store_dwordx4 v[34:35], v[16:19], off
	global_store_dwordx4 v[34:35], v[20:23], off offset:256
	v_lshlrev_b64 v[18:19], 13, v[32:33]
	v_lshl_add_u64 v[18:19], s[28:29], 0, v[18:19]
	v_lshl_add_u64 v[18:19], v[18:19], 0, v[146:147]
	v_mov_b32_e32 v16, v235
	s_nop 0
	v_pk_mul_f32 v[14:15], v[14:15], v[16:17] op_sel_hi:[1,0]
	v_pk_mul_f32 v[12:13], v[12:13], v[16:17] op_sel_hi:[1,0]
	v_pk_mul_f32 v[10:11], v[10:11], v[16:17] op_sel_hi:[1,0]
	v_pk_mul_f32 v[8:9], v[8:9], v[16:17] op_sel_hi:[1,0]
	v_pk_mul_f32 v[6:7], v[6:7], v[16:17] op_sel_hi:[1,0]
	v_pk_mul_f32 v[4:5], v[4:5], v[16:17] op_sel_hi:[1,0]
	v_pk_mul_f32 v[2:3], v[2:3], v[16:17] op_sel_hi:[1,0]
	v_pk_mul_f32 v[0:1], v[0:1], v[16:17] op_sel_hi:[1,0]
	v_max_f32_e32 v12, 0, v12
	v_max_f32_e32 v8, 0, v8
	v_max_f32_e32 v13, 0, v13
	v_max_f32_e32 v9, 0, v9
	v_max_f32_e32 v14, 0, v14
	v_max_f32_e32 v10, 0, v10
	v_max_f32_e32 v15, 0, v15
	v_max_f32_e32 v11, 0, v11
	v_max_f32_e32 v4, 0, v4
	v_max_f32_e32 v0, 0, v0
	v_max_f32_e32 v5, 0, v5
	v_max_f32_e32 v1, 0, v1
	v_max_f32_e32 v6, 0, v6
	v_max_f32_e32 v2, 0, v2
	v_max_f32_e32 v7, 0, v7
	v_max_f32_e32 v3, 0, v3
	v_pk_mul_f32 v[12:13], v[12:13], v[12:13]
	v_pk_mul_f32 v[8:9], v[8:9], v[8:9]
	v_pk_mul_f32 v[14:15], v[14:15], v[14:15]
	v_pk_mul_f32 v[10:11], v[10:11], v[10:11]
	v_pk_mul_f32 v[4:5], v[4:5], v[4:5]
	v_pk_mul_f32 v[16:17], v[0:1], v[0:1]
	v_pk_mul_f32 v[6:7], v[6:7], v[6:7]
	v_pk_mul_f32 v[20:21], v[2:3], v[2:3]
	v_cvt_pk_bf16_f32 v0, v12, v13
	v_cvt_pk_bf16_f32 v1, v14, v15
	v_cvt_pk_bf16_f32 v2, v8, v9
	v_cvt_pk_bf16_f32 v3, v10, v11
	v_cvt_pk_bf16_f32 v4, v4, v5
	v_cvt_pk_bf16_f32 v5, v6, v7
	v_cvt_pk_bf16_f32 v6, v16, v17
	v_cvt_pk_bf16_f32 v7, v20, v21
	global_store_dwordx4 v[18:19], v[0:3], off
	global_store_dwordx4 v[18:19], v[4:7], off offset:256
	s_cbranch_vccnz .LBB0_387
	s_andn2_b64 vcc, exec, s[6:7]
	s_cbranch_vccnz .LBB0_386
	s_mov_b32 s100, 1
	s_branch .LBB0_386
